# RG-LRU conv blocks regenerated with all tap/bias LDS reads up front (bit-exact); layer-0 context attention units re-assigned to blocks with the short RG-LRU range
# speedup vs baseline: 1.0251x; 1.0070x over previous
; __device__ __forceinline__ unsigned cvt_pk_bf16(float lo, float hi) { unsigned r; asm volatile("v_cvt_pk_bf16_f32 %0, %1, %2" : "=v"(r) : "v"(lo), "v"(hi)); return r; }
; __device__ __forceinline__ int crow(int r, int hi) { return (r & 3) + 8 * (r >> 2) + 4 * hi; }
; __device__ __forceinline__ void attn_unit(char* lds, const int tid, const bf16_t* Qb, bf16_t* Ob, const bf16_t* KVb, int qrow0, int t0, int b, int kvh, const float* sink_l) {
;     ...
;     for (int r = 0; r < 16; ++r) { const int orow = crow(r, hi); const float rl = __builtin_amdgcn_rcpf(li_l[orow]);
; #pragma unroll
;         for (int d0 = 0; d0 < 4; ++d0) { const unsigned w = cvt_pk_bf16(o[d0][r] * rl, 0.f); Ow[(size_t)orow * 1024 + d0 * 32 + r32] = (bf16_t)(w & 0xffffu); } }
; __device__ __forceinline__ void attn_phase(const Ctx& F, int l, const bf16_t* Qb, bf16_t* Ob, const bf16_t* KVb, bool with_ctx) {
;     ...
;     for (int u = F.bid; u < nun; u += F.G) {
;         if (u < nlat) { const int qb = u & 63, kvh = (u >> 6) & 1, b = u >> 7; att::attn_unit(F.ldsg, F.tid, Qb, Ob, KVb, b * SEQ + qb * 64, qb * 64, b, kvh, sink); }
;         else { const int v = u - nlat, cb = v & 3, kvh = (v >> 2) & 1, b = v >> 3; att::attn_unit(F.ldsg, F.tid, Qb, Ob, KVb, ML + b * CTX + cb * 64, -1, b, kvh, sink); }
.LBB0_418:
	v_lshlrev_b32_e32 v32, 1, v170
	v_lshl_add_u64 v[2:3], v[80:81], 0, v[32:33]
	s_add_i32 s5, s5, s3
	s_add_i32 s4, s4, s46
	s_add_i32 s1, s1, s47
	v_lshl_add_u64 v[2:3], v[2:3], 0, v[208:209]
	s_cmpk_lt_i32 s5, 0x200
	s_cbranch_scc1 .Lattn_nomap
	s_cmpk_lg_i32 s0, 0x220
	s_cbranch_scc1 .Lattn_nomap
	s_cmpk_lg_i32 s3, 0x100
	s_cbranch_scc1 .Lattn_nomap
	s_cmpk_gt_i32 s5, 0x2ff
	s_cbranch_scc1 .Lattn_nomap
	v_readlane_b32 s12, v252, 0
	s_nop 3
	s_bitcmp1_b32 s12, 2
	s_cbranch_scc0 .Lattn_none
	s_cmp_lt_u32 s12, 64
	s_cbranch_scc0 .Lattn_none
	s_lshr_b32 s13, s12, 3
	s_lshl_b32 s13, s13, 2
	s_and_b32 s12, s12, 3
	s_or_b32 s12, s12, s13
	s_add_i32 s5, s12, 0x200
	s_lshl_b32 s4, s5, 5
	s_lshl_b32 s1, s5, 6
	s_branch .Lattn_nomap
.Lattn_none:
	s_movk_i32 s5, 0x7000
.Lattn_nomap:
	s_cmp_lt_i32 s5, s0
	global_store_short v[2:3], v0, off offset:192
	s_cbranch_scc0 .LBB0_451

; #define LAS __attribute__((address_space(3)))
; __device__ __forceinline__ unsigned cvt_pk_bf16(float lo, float hi) { unsigned r; asm volatile("v_cvt_pk_bf16_f32 %0, %1, %2" : "=v"(r) : "v"(lo), "v"(hi)); return r; }
; __device__ __forceinline__ float bflo(unsigned w) { return __uint_as_float(w << 16); }
; __device__ __forceinline__ float bfhi(unsigned w) { return __uint_as_float(w & 0xffff0000u); }
; template <int PASS>
; __device__ __forceinline__ void rglru_phase(const Ctx& F, int l, const bf16_t* XRb, bf16_t* GRb, bool latent_only = false) {
;     ...
;             {
;                 float y[16];
; #pragma unroll
;                 for (int e = 0; e < 4; ++e) { const f32x4 bv = *(const LAS f32x4*)(CW + 512 + cs + 4 * e); y[4 * e] = bv[0]; y[4 * e + 1] = bv[1]; y[4 * e + 2] = bv[2]; y[4 * e + 3] = bv[3]; }
; #pragma unroll
;                 for (int k = 0; k < 4; ++k)
; #pragma unroll
;                     for (int e = 0; e < 4; ++e) { const f32x4 wv = *(const LAS f32x4*)(CW + k * 128 + cs + 4 * e); const unsigned w0 = xin[k][e >> 1][2 * (e & 1)], w1 = xin[k][e >> 1][2 * (e & 1) + 1];
;                         y[4 * e] += bflo(w0) * wv[0]; y[4 * e + 1] += bfhi(w0) * wv[1]; y[4 * e + 2] += bflo(w1) * wv[2]; y[4 * e + 3] += bfhi(w1) * wv[3]; }
;                 u32x4 o0, o1; o0.x = cvt_pk_bf16(y[0], y[1]); o0.y = cvt_pk_bf16(y[2], y[3]); o0.z = cvt_pk_bf16(y[4], y[5]); o0.w = cvt_pk_bf16(y[6], y[7]);
;                 o1.x = cvt_pk_bf16(y[8], y[9]); o1.y = cvt_pk_bf16(y[10], y[11]); o1.z = cvt_pk_bf16(y[12], y[13]); o1.w = cvt_pk_bf16(y[14], y[15]);
;                 *(LAS u32x4*)(XT + tt * XT_LD + cs) = o0; *(LAS u32x4*)(XT + tt * XT_LD + cs + 8) = o1;
;             }
.LBB0_510:
	v_add_u32_e32 v32, v145, v144
	s_waitcnt lgkmcnt(0)
	s_barrier
	ds_read_b128 v[116:119], v32 offset:19456
	ds_read_b128 v[120:123], v32 offset:19472
	ds_read_b128 v[124:127], v32 offset:19488
	ds_read_b128 v[128:131], v32 offset:19504
	ds_read_b128 v[132:135], v32 offset:17408
	ds_read_b128 v[136:139], v32 offset:17424
	ds_read_b128 v[160:163], v32 offset:17440
	ds_read_b128 v[188:191], v32 offset:17456
	ds_read_b128 v[192:195], v32 offset:17920
	ds_read_b128 v[196:199], v32 offset:17936
	ds_read_b128 v[200:203], v32 offset:17952
	ds_read_b128 v[204:207], v32 offset:17968
	ds_read_b128 v[208:211], v32 offset:18432
	ds_read_b128 v[212:215], v32 offset:18448
	ds_read_b128 v[220:223], v32 offset:18464
	ds_read_b128 v[224:227], v32 offset:18480
	ds_read_b128 v[228:231], v32 offset:18944
	ds_read_b128 v[232:235], v32 offset:18960
	ds_read_b128 v[236:239], v32 offset:18976
	ds_read_b128 v[248:251], v32 offset:18992
	s_add_i32 s8, s38, 1
	s_cmp_ge_u32 s8, s13
	s_mov_b64 s[18:19], -1
	s_cselect_b64 s[62:63], -1, 0
	s_waitcnt lgkmcnt(12)
	v_lshlrev_b32_e32 v34, 16, v76
	v_and_b32_e32 v35, 0xffff0000, v76
	v_pk_mul_f32 v[34:35], v[132:133], v[34:35]
	v_pk_add_f32 v[116:117], v[116:117], v[34:35]
	v_lshlrev_b32_e32 v164, 16, v77
	v_and_b32_e32 v165, 0xffff0000, v77
	v_pk_mul_f32 v[164:165], v[134:135], v[164:165]
	v_pk_add_f32 v[118:119], v[118:119], v[164:165]
	v_lshlrev_b32_e32 v240, 16, v78
	v_and_b32_e32 v241, 0xffff0000, v78
	v_pk_mul_f32 v[240:241], v[136:137], v[240:241]
	v_pk_add_f32 v[120:121], v[120:121], v[240:241]
	v_lshlrev_b32_e32 v34, 16, v79
	v_and_b32_e32 v35, 0xffff0000, v79
	v_pk_mul_f32 v[34:35], v[138:139], v[34:35]
	v_pk_add_f32 v[122:123], v[122:123], v[34:35]
	v_lshlrev_b32_e32 v164, 16, v72
	v_and_b32_e32 v165, 0xffff0000, v72
	v_pk_mul_f32 v[164:165], v[160:161], v[164:165]
	v_pk_add_f32 v[124:125], v[124:125], v[164:165]
	v_lshlrev_b32_e32 v240, 16, v73
	v_and_b32_e32 v241, 0xffff0000, v73
	v_pk_mul_f32 v[240:241], v[162:163], v[240:241]
	v_pk_add_f32 v[126:127], v[126:127], v[240:241]
	v_lshlrev_b32_e32 v34, 16, v74
	v_and_b32_e32 v35, 0xffff0000, v74
	v_pk_mul_f32 v[34:35], v[188:189], v[34:35]
	v_pk_add_f32 v[128:129], v[128:129], v[34:35]
	v_lshlrev_b32_e32 v164, 16, v75
	v_and_b32_e32 v165, 0xffff0000, v75
	v_pk_mul_f32 v[164:165], v[190:191], v[164:165]
	v_pk_add_f32 v[130:131], v[130:131], v[164:165]
	s_waitcnt lgkmcnt(8)
	v_lshlrev_b32_e32 v240, 16, v68
	v_and_b32_e32 v241, 0xffff0000, v68
	v_pk_mul_f32 v[240:241], v[192:193], v[240:241]
	v_pk_add_f32 v[116:117], v[116:117], v[240:241]
	v_lshlrev_b32_e32 v34, 16, v69
	v_and_b32_e32 v35, 0xffff0000, v69
	v_pk_mul_f32 v[34:35], v[194:195], v[34:35]
	v_pk_add_f32 v[118:119], v[118:119], v[34:35]
	v_lshlrev_b32_e32 v164, 16, v70
	v_and_b32_e32 v165, 0xffff0000, v70
	v_pk_mul_f32 v[164:165], v[196:197], v[164:165]
	v_pk_add_f32 v[120:121], v[120:121], v[164:165]
	v_lshlrev_b32_e32 v240, 16, v71
	v_and_b32_e32 v241, 0xffff0000, v71
	v_pk_mul_f32 v[240:241], v[198:199], v[240:241]
	v_pk_add_f32 v[122:123], v[122:123], v[240:241]
	v_lshlrev_b32_e32 v34, 16, v80
	v_and_b32_e32 v35, 0xffff0000, v80
	v_pk_mul_f32 v[34:35], v[200:201], v[34:35]
	v_pk_add_f32 v[124:125], v[124:125], v[34:35]
	v_lshlrev_b32_e32 v164, 16, v81
	v_and_b32_e32 v165, 0xffff0000, v81
	v_pk_mul_f32 v[164:165], v[202:203], v[164:165]
	v_pk_add_f32 v[126:127], v[126:127], v[164:165]
	v_lshlrev_b32_e32 v240, 16, v82
	v_and_b32_e32 v241, 0xffff0000, v82
	v_pk_mul_f32 v[240:241], v[204:205], v[240:241]
	v_pk_add_f32 v[128:129], v[128:129], v[240:241]
	v_lshlrev_b32_e32 v34, 16, v83
	v_and_b32_e32 v35, 0xffff0000, v83
	v_pk_mul_f32 v[34:35], v[206:207], v[34:35]
	v_pk_add_f32 v[130:131], v[130:131], v[34:35]
	s_waitcnt lgkmcnt(4)
	v_lshlrev_b32_e32 v164, 16, v88
	v_and_b32_e32 v165, 0xffff0000, v88
	v_pk_mul_f32 v[164:165], v[208:209], v[164:165]
	v_pk_add_f32 v[116:117], v[116:117], v[164:165]
	v_lshlrev_b32_e32 v240, 16, v89
	v_and_b32_e32 v241, 0xffff0000, v89
	v_pk_mul_f32 v[240:241], v[210:211], v[240:241]
	v_pk_add_f32 v[118:119], v[118:119], v[240:241]
	v_lshlrev_b32_e32 v34, 16, v90
	v_and_b32_e32 v35, 0xffff0000, v90
	v_pk_mul_f32 v[34:35], v[212:213], v[34:35]
	v_pk_add_f32 v[120:121], v[120:121], v[34:35]
	v_lshlrev_b32_e32 v164, 16, v91
	v_and_b32_e32 v165, 0xffff0000, v91
	v_pk_mul_f32 v[164:165], v[214:215], v[164:165]
	v_pk_add_f32 v[122:123], v[122:123], v[164:165]
	v_lshlrev_b32_e32 v240, 16, v84
	v_and_b32_e32 v241, 0xffff0000, v84
	v_pk_mul_f32 v[240:241], v[220:221], v[240:241]
	v_pk_add_f32 v[124:125], v[124:125], v[240:241]
	v_lshlrev_b32_e32 v34, 16, v85
	v_and_b32_e32 v35, 0xffff0000, v85
	v_pk_mul_f32 v[34:35], v[222:223], v[34:35]
	v_pk_add_f32 v[126:127], v[126:127], v[34:35]
	v_lshlrev_b32_e32 v164, 16, v86
	v_and_b32_e32 v165, 0xffff0000, v86
	v_pk_mul_f32 v[164:165], v[224:225], v[164:165]
	v_pk_add_f32 v[128:129], v[128:129], v[164:165]
	v_lshlrev_b32_e32 v240, 16, v87
	v_and_b32_e32 v241, 0xffff0000, v87
	v_pk_mul_f32 v[240:241], v[226:227], v[240:241]
	v_pk_add_f32 v[130:131], v[130:131], v[240:241]
	s_waitcnt lgkmcnt(0)
	v_lshlrev_b32_e32 v34, 16, v92
	v_and_b32_e32 v35, 0xffff0000, v92
	v_pk_mul_f32 v[34:35], v[228:229], v[34:35]
	v_pk_add_f32 v[116:117], v[116:117], v[34:35]
	v_lshlrev_b32_e32 v164, 16, v93
	v_and_b32_e32 v165, 0xffff0000, v93
	v_pk_mul_f32 v[164:165], v[230:231], v[164:165]
	v_pk_add_f32 v[118:119], v[118:119], v[164:165]
	v_lshlrev_b32_e32 v240, 16, v94
	v_and_b32_e32 v241, 0xffff0000, v94
	v_pk_mul_f32 v[240:241], v[232:233], v[240:241]
	v_pk_add_f32 v[120:121], v[120:121], v[240:241]
	v_lshlrev_b32_e32 v34, 16, v95
	v_and_b32_e32 v35, 0xffff0000, v95
	v_pk_mul_f32 v[34:35], v[234:235], v[34:35]
	v_pk_add_f32 v[122:123], v[122:123], v[34:35]
	v_lshlrev_b32_e32 v164, 16, v96
	v_and_b32_e32 v165, 0xffff0000, v96
	v_pk_mul_f32 v[164:165], v[236:237], v[164:165]
	v_pk_add_f32 v[124:125], v[124:125], v[164:165]
	v_lshlrev_b32_e32 v240, 16, v97
	v_and_b32_e32 v241, 0xffff0000, v97
	v_pk_mul_f32 v[240:241], v[238:239], v[240:241]
	v_pk_add_f32 v[126:127], v[126:127], v[240:241]
	v_lshlrev_b32_e32 v34, 16, v98
	v_and_b32_e32 v35, 0xffff0000, v98
	v_pk_mul_f32 v[34:35], v[248:249], v[34:35]
	v_pk_add_f32 v[128:129], v[128:129], v[34:35]
	v_lshlrev_b32_e32 v164, 16, v99
	v_and_b32_e32 v165, 0xffff0000, v99
	v_pk_mul_f32 v[164:165], v[250:251], v[164:165]
	v_pk_add_f32 v[130:131], v[130:131], v[164:165]
	v_cvt_pk_bf16_f32 v132, v116, v117
	v_cvt_pk_bf16_f32 v133, v118, v119
	v_cvt_pk_bf16_f32 v134, v120, v121
	v_cvt_pk_bf16_f32 v135, v122, v123
	v_cvt_pk_bf16_f32 v136, v124, v125
	v_cvt_pk_bf16_f32 v137, v126, v127
	v_cvt_pk_bf16_f32 v138, v128, v129
	v_cvt_pk_bf16_f32 v139, v130, v131
	ds_write_b128 v179, v[132:135]
	ds_write_b128 v179, v[136:139] offset:16
	s_cmp_lt_u32 s8, s13
	s_waitcnt lgkmcnt(0)
	s_barrier
	s_cbranch_scc1 .LBB0_512
	s_add_i32 s33, s39, 64
	s_mov_b64 s[18:19], 0

; #define LAS __attribute__((address_space(3)))
; __device__ __forceinline__ unsigned cvt_pk_bf16(float lo, float hi) { unsigned r; asm volatile("v_cvt_pk_bf16_f32 %0, %1, %2" : "=v"(r) : "v"(lo), "v"(hi)); return r; }
; __device__ __forceinline__ float bflo(unsigned w) { return __uint_as_float(w << 16); }
; __device__ __forceinline__ float bfhi(unsigned w) { return __uint_as_float(w & 0xffff0000u); }
; template <int PASS>
; __device__ __forceinline__ void rglru_phase(const Ctx& F, int l, const bf16_t* XRb, bf16_t* GRb, bool latent_only = false) {
;     ...
;             {
;                 float y[16];
; #pragma unroll
;                 for (int e = 0; e < 4; ++e) { const f32x4 bv = *(const LAS f32x4*)(CW + 512 + cs + 4 * e); y[4 * e] = bv[0]; y[4 * e + 1] = bv[1]; y[4 * e + 2] = bv[2]; y[4 * e + 3] = bv[3]; }
; #pragma unroll
;                 for (int k = 0; k < 4; ++k)
; #pragma unroll
;                     for (int e = 0; e < 4; ++e) { const f32x4 wv = *(const LAS f32x4*)(CW + k * 128 + cs + 4 * e); const unsigned w0 = xin[k][e >> 1][2 * (e & 1)], w1 = xin[k][e >> 1][2 * (e & 1) + 1];
;                         y[4 * e] += bflo(w0) * wv[0]; y[4 * e + 1] += bfhi(w0) * wv[1]; y[4 * e + 2] += bflo(w1) * wv[2]; y[4 * e + 3] += bfhi(w1) * wv[3]; }
;                 u32x4 o0, o1; o0.x = cvt_pk_bf16(y[0], y[1]); o0.y = cvt_pk_bf16(y[2], y[3]); o0.z = cvt_pk_bf16(y[4], y[5]); o0.w = cvt_pk_bf16(y[6], y[7]);
;                 o1.x = cvt_pk_bf16(y[8], y[9]); o1.y = cvt_pk_bf16(y[10], y[11]); o1.z = cvt_pk_bf16(y[12], y[13]); o1.w = cvt_pk_bf16(y[14], y[15]);
;                 *(LAS u32x4*)(XT + tt * XT_LD + cs) = o0; *(LAS u32x4*)(XT + tt * XT_LD + cs + 8) = o1;
;             }
.LBB0_560:
	v_add_u32_e32 v32, v137, v136
	s_waitcnt lgkmcnt(0)
	s_barrier
	ds_read_b128 v[116:119], v32 offset:19456
	ds_read_b128 v[120:123], v32 offset:19472
	ds_read_b128 v[124:127], v32 offset:19488
	ds_read_b128 v[128:131], v32 offset:19504
	ds_read_b128 v[144:147], v32 offset:17408
	ds_read_b128 v[148:151], v32 offset:17424
	ds_read_b128 v[152:155], v32 offset:17440
	ds_read_b128 v[160:163], v32 offset:17456
	ds_read_b128 v[182:185], v32 offset:17920
	ds_read_b128 v[186:189], v32 offset:17936
	ds_read_b128 v[190:193], v32 offset:17952
	ds_read_b128 v[194:197], v32 offset:17968
	ds_read_b128 v[198:201], v32 offset:18432
	ds_read_b128 v[206:209], v32 offset:18448
	ds_read_b128 v[210:213], v32 offset:18464
	ds_read_b128 v[220:223], v32 offset:18480
	ds_read_b128 v[224:227], v32 offset:18944
	ds_read_b128 v[228:231], v32 offset:18960
	ds_read_b128 v[232:235], v32 offset:18976
	ds_read_b128 v[236:239], v32 offset:18992
	s_waitcnt vmcnt(0)
	s_add_i32 s27, s33, 1
	s_cmp_ge_u32 s27, s26
	s_cselect_b64 s[12:13], -1, 0
	s_waitcnt lgkmcnt(12)
	v_lshlrev_b32_e32 v34, 16, v72
	v_and_b32_e32 v35, 0xffff0000, v72
	v_pk_mul_f32 v[34:35], v[144:145], v[34:35]
	v_pk_add_f32 v[116:117], v[116:117], v[34:35]
	v_lshlrev_b32_e32 v164, 16, v73
	v_and_b32_e32 v165, 0xffff0000, v73
	v_pk_mul_f32 v[164:165], v[146:147], v[164:165]
	v_pk_add_f32 v[118:119], v[118:119], v[164:165]
	v_lshlrev_b32_e32 v240, 16, v74
	v_and_b32_e32 v241, 0xffff0000, v74
	v_pk_mul_f32 v[240:241], v[148:149], v[240:241]
	v_pk_add_f32 v[120:121], v[120:121], v[240:241]
	v_lshlrev_b32_e32 v34, 16, v75
	v_and_b32_e32 v35, 0xffff0000, v75
	v_pk_mul_f32 v[34:35], v[150:151], v[34:35]
	v_pk_add_f32 v[122:123], v[122:123], v[34:35]
	v_lshlrev_b32_e32 v164, 16, v68
	v_and_b32_e32 v165, 0xffff0000, v68
	v_pk_mul_f32 v[164:165], v[152:153], v[164:165]
	v_pk_add_f32 v[124:125], v[124:125], v[164:165]
	v_lshlrev_b32_e32 v240, 16, v69
	v_and_b32_e32 v241, 0xffff0000, v69
	v_pk_mul_f32 v[240:241], v[154:155], v[240:241]
	v_pk_add_f32 v[126:127], v[126:127], v[240:241]
	v_lshlrev_b32_e32 v34, 16, v70
	v_and_b32_e32 v35, 0xffff0000, v70
	v_pk_mul_f32 v[34:35], v[160:161], v[34:35]
	v_pk_add_f32 v[128:129], v[128:129], v[34:35]
	v_lshlrev_b32_e32 v164, 16, v71
	v_and_b32_e32 v165, 0xffff0000, v71
	v_pk_mul_f32 v[164:165], v[162:163], v[164:165]
	v_pk_add_f32 v[130:131], v[130:131], v[164:165]
	s_waitcnt lgkmcnt(8)
	v_lshlrev_b32_e32 v240, 16, v80
	v_and_b32_e32 v241, 0xffff0000, v80
	v_pk_mul_f32 v[240:241], v[182:183], v[240:241]
	v_pk_add_f32 v[116:117], v[116:117], v[240:241]
	v_lshlrev_b32_e32 v34, 16, v81
	v_and_b32_e32 v35, 0xffff0000, v81
	v_pk_mul_f32 v[34:35], v[184:185], v[34:35]
	v_pk_add_f32 v[118:119], v[118:119], v[34:35]
	v_lshlrev_b32_e32 v164, 16, v82
	v_and_b32_e32 v165, 0xffff0000, v82
	v_pk_mul_f32 v[164:165], v[186:187], v[164:165]
	v_pk_add_f32 v[120:121], v[120:121], v[164:165]
	v_lshlrev_b32_e32 v240, 16, v83
	v_and_b32_e32 v241, 0xffff0000, v83
	v_pk_mul_f32 v[240:241], v[188:189], v[240:241]
	v_pk_add_f32 v[122:123], v[122:123], v[240:241]
	v_lshlrev_b32_e32 v34, 16, v76
	v_and_b32_e32 v35, 0xffff0000, v76
	v_pk_mul_f32 v[34:35], v[190:191], v[34:35]
	v_pk_add_f32 v[124:125], v[124:125], v[34:35]
	v_lshlrev_b32_e32 v164, 16, v77
	v_and_b32_e32 v165, 0xffff0000, v77
	v_pk_mul_f32 v[164:165], v[192:193], v[164:165]
	v_pk_add_f32 v[126:127], v[126:127], v[164:165]
	v_lshlrev_b32_e32 v240, 16, v78
	v_and_b32_e32 v241, 0xffff0000, v78
	v_pk_mul_f32 v[240:241], v[194:195], v[240:241]
	v_pk_add_f32 v[128:129], v[128:129], v[240:241]
	v_lshlrev_b32_e32 v34, 16, v79
	v_and_b32_e32 v35, 0xffff0000, v79
	v_pk_mul_f32 v[34:35], v[196:197], v[34:35]
	v_pk_add_f32 v[130:131], v[130:131], v[34:35]
	s_waitcnt lgkmcnt(4)
	v_lshlrev_b32_e32 v164, 16, v96
	v_and_b32_e32 v165, 0xffff0000, v96
	v_pk_mul_f32 v[164:165], v[198:199], v[164:165]
	v_pk_add_f32 v[116:117], v[116:117], v[164:165]
	v_lshlrev_b32_e32 v240, 16, v97
	v_and_b32_e32 v241, 0xffff0000, v97
	v_pk_mul_f32 v[240:241], v[200:201], v[240:241]
	v_pk_add_f32 v[118:119], v[118:119], v[240:241]
	v_lshlrev_b32_e32 v34, 16, v98
	v_and_b32_e32 v35, 0xffff0000, v98
	v_pk_mul_f32 v[34:35], v[206:207], v[34:35]
	v_pk_add_f32 v[120:121], v[120:121], v[34:35]
	v_lshlrev_b32_e32 v164, 16, v99
	v_and_b32_e32 v165, 0xffff0000, v99
	v_pk_mul_f32 v[164:165], v[208:209], v[164:165]
	v_pk_add_f32 v[122:123], v[122:123], v[164:165]
	v_lshlrev_b32_e32 v240, 16, v92
	v_and_b32_e32 v241, 0xffff0000, v92
	v_pk_mul_f32 v[240:241], v[210:211], v[240:241]
	v_pk_add_f32 v[124:125], v[124:125], v[240:241]
	v_lshlrev_b32_e32 v34, 16, v93
	v_and_b32_e32 v35, 0xffff0000, v93
	v_pk_mul_f32 v[34:35], v[212:213], v[34:35]
	v_pk_add_f32 v[126:127], v[126:127], v[34:35]
	v_lshlrev_b32_e32 v164, 16, v94
	v_and_b32_e32 v165, 0xffff0000, v94
	v_pk_mul_f32 v[164:165], v[220:221], v[164:165]
	v_pk_add_f32 v[128:129], v[128:129], v[164:165]
	v_lshlrev_b32_e32 v240, 16, v95
	v_and_b32_e32 v241, 0xffff0000, v95
	v_pk_mul_f32 v[240:241], v[222:223], v[240:241]
	v_pk_add_f32 v[130:131], v[130:131], v[240:241]
	s_waitcnt lgkmcnt(0)
	v_lshlrev_b32_e32 v34, 16, v104
	v_and_b32_e32 v35, 0xffff0000, v104
	v_pk_mul_f32 v[34:35], v[224:225], v[34:35]
	v_pk_add_f32 v[116:117], v[116:117], v[34:35]
	v_lshlrev_b32_e32 v164, 16, v105
	v_and_b32_e32 v165, 0xffff0000, v105
	v_pk_mul_f32 v[164:165], v[226:227], v[164:165]
	v_pk_add_f32 v[118:119], v[118:119], v[164:165]
	v_lshlrev_b32_e32 v240, 16, v106
	v_and_b32_e32 v241, 0xffff0000, v106
	v_pk_mul_f32 v[240:241], v[228:229], v[240:241]
	v_pk_add_f32 v[120:121], v[120:121], v[240:241]
	v_lshlrev_b32_e32 v34, 16, v107
	v_and_b32_e32 v35, 0xffff0000, v107
	v_pk_mul_f32 v[34:35], v[230:231], v[34:35]
	v_pk_add_f32 v[122:123], v[122:123], v[34:35]
	v_lshlrev_b32_e32 v164, 16, v100
	v_and_b32_e32 v165, 0xffff0000, v100
	v_pk_mul_f32 v[164:165], v[232:233], v[164:165]
	v_pk_add_f32 v[124:125], v[124:125], v[164:165]
	v_lshlrev_b32_e32 v240, 16, v101
	v_and_b32_e32 v241, 0xffff0000, v101
	v_pk_mul_f32 v[240:241], v[234:235], v[240:241]
	v_pk_add_f32 v[126:127], v[126:127], v[240:241]
	v_lshlrev_b32_e32 v34, 16, v102
	v_and_b32_e32 v35, 0xffff0000, v102
	v_pk_mul_f32 v[34:35], v[236:237], v[34:35]
	v_pk_add_f32 v[128:129], v[128:129], v[34:35]
	v_lshlrev_b32_e32 v164, 16, v103
	v_and_b32_e32 v165, 0xffff0000, v103
	v_pk_mul_f32 v[164:165], v[238:239], v[164:165]
	v_pk_add_f32 v[130:131], v[130:131], v[164:165]
	v_cvt_pk_bf16_f32 v144, v116, v117
	v_cvt_pk_bf16_f32 v145, v118, v119
	v_cvt_pk_bf16_f32 v146, v120, v121
	v_cvt_pk_bf16_f32 v147, v122, v123
	v_cvt_pk_bf16_f32 v148, v124, v125
	v_cvt_pk_bf16_f32 v149, v126, v127
	v_cvt_pk_bf16_f32 v150, v128, v129
	v_cvt_pk_bf16_f32 v151, v130, v131
	ds_write_b128 v177, v[144:147]
	ds_write_b128 v177, v[148:151] offset:16
	s_and_b64 vcc, exec, s[12:13]
	s_waitcnt lgkmcnt(0)
	s_barrier
; template <int PASS>
; __device__ __forceinline__ void rglru_phase(const Ctx& F, int l, const bf16_t* XRb, bf16_t* GRb, bool latent_only = false) {
;     ...
;             if (c + 1 < c1) RG_LOADX(c + 1);
	s_cbranch_vccnz .LBB0_570
	s_add_i32 s18, s8, 0x100
	s_cmp_lt_u32 s33, 3
	s_cselect_b32 s18, s18, s8
	v_add_u32_e32 v102, s18, v158
	s_cselect_b32 s38, 0x100, s10
	v_add_u32_e32 v32, -2, v102
	v_mov_b32_e32 v76, 0
	v_mov_b32_e32 v77, v33
	v_cmp_lt_i32_e32 vcc, 1, v102
	v_cmp_gt_i32_e64 s[52:53], s38, v32
	v_mov_b32_e32 v78, v33
	v_mov_b32_e32 v79, v33
	v_mov_b64_e32 v[68:69], v[76:77]
	v_mov_b64_e32 v[72:73], v[76:77]
	s_cselect_b32 s33, s22, s23
	s_and_b64 s[52:53], vcc, s[52:53]
	v_mov_b64_e32 v[70:71], v[78:79]
	v_mov_b64_e32 v[74:75], v[78:79]
	s_and_saveexec_b64 s[18:19], s[52:53]
	s_cbranch_execz .LBB0_563
	v_add_u32_e32 v34, s33, v32
	v_ashrrev_i32_e32 v35, 31, v34
	v_lshlrev_b64 v[34:35], 11, v[34:35]
	v_lshl_add_u64 v[34:35], v[140:141], 0, v[34:35]
	global_load_dwordx4 v[68:71], v[34:35], off offset:16
	global_load_dwordx4 v[72:75], v[34:35], off
